# barrier spin loops poll without s_sleep (s_nop 7 instead) on top of v104
# baseline (speedup 1.0000x reference)
; __device__ __forceinline__ unsigned xb_ld(unsigned* p)              { return __hip_atomic_load(p, __ATOMIC_RELAXED, __HIP_MEMORY_SCOPE_AGENT); }
; #define XB_SPIN(cond, bar) do { unsigned _sp = 0; while (cond) { __builtin_amdgcn_s_sleep(1); \
;     if ((++_sp & 255u) == 0u) { if (xb_ld(&(bar)[XB_TMO])) break; if (_sp > XB_SPIN_CAP) { atomicAdd(&(bar)[XB_TMO], 1u); break; } } } } while (0)
; __device__ __forceinline__ void xcd_barrier(unsigned* bar, volatile LAS unsigned* st, const int tid) {
;     ...
;             XB_SPIN(xb_ld(&bar[XB_XGEN(x)]) == gen, bar);
.LBB0_72:
	s_and_b32 s27, s3, 0xff
	s_mov_b64 s[52:53], -1
	s_cmp_lg_u32 s27, 0
	s_mov_b64 s[58:59], -1
	s_nop 7
	s_cbranch_scc0 .LBB0_75
	s_and_b64 vcc, exec, s[58:59]
	s_cbranch_vccz .LBB0_71

; __device__ __forceinline__ unsigned xb_ld(unsigned* p)              { return __hip_atomic_load(p, __ATOMIC_RELAXED, __HIP_MEMORY_SCOPE_AGENT); }
; #define XB_SPIN(cond, bar) do { unsigned _sp = 0; while (cond) { __builtin_amdgcn_s_sleep(1); \
;     if ((++_sp & 255u) == 0u) { if (xb_ld(&(bar)[XB_TMO])) break; if (_sp > XB_SPIN_CAP) { atomicAdd(&(bar)[XB_TMO], 1u); break; } } } } while (0)
; __device__ __forceinline__ void xcd_barrier(unsigned* bar, volatile LAS unsigned* st, const int tid) {
;     ...
;             else XB_SPIN(xb_ld(&bar[XB_TOPGEN]) == tg, bar);
.LBB0_89:
	s_and_b32 s27, s3, 0xff
	s_mov_b64 s[24:25], -1
	s_cmp_lg_u32 s27, 0
	s_mov_b64 s[48:49], -1
	s_nop 7
	s_cbranch_scc0 .LBB0_92
	s_and_b64 vcc, exec, s[48:49]
	s_cbranch_vccz .LBB0_88
